# v78 (xprep 4 rows/iter) + XCD-hierarchical grid barrier: per-XCC arrival counters, one L2 write-back per XCD by its last arriver, every wave drains vmcnt before arrival
# speedup vs baseline: 1.0757x; 1.0559x over previous
.LBB0_68:
	s_or_b64 exec, exec, s[14:15]
	v_cmp_gt_i32_e32 vcc, 0xc00, v2
	v_ashrrev_i32_e32 v3, 31, v2
	s_and_saveexec_b64 s[4:5], vcc
	s_cbranch_execz .LBB0_70
	v_lshl_add_u64 v[4:5], v[2:3], 2, s[84:85]
	v_add_co_u32_e32 v4, vcc, 0x2ce10000, v4
	v_mov_b32_e32 v1, 0
	s_nop 0
	v_addc_co_u32_e32 v5, vcc, 0, v5, vcc
	global_store_dword v[4:5], v1, off

.LBB0_83:
	s_or_b64 exec, exec, s[4:5]
	v_mov_b32_e32 v1, v11
	s_mov_b32 s2, 0x10000
	v_ashrrev_i32_e32 v2, 6, v11
	v_lshl_add_u32 v2, s82, 2, v2
	v_cmp_gt_i32_e32 vcc, s2, v2
	s_and_saveexec_b64 s[4:5], vcc
	s_cbranch_execz .LBB0_88
	v_and_b32_e32 v15, 63, v1
	v_mbcnt_lo_u32_b32 v1, -1, 0
	v_mbcnt_hi_u32_b32 v3, -1, v1
	v_and_b32_e32 v1, 64, v3
	v_add_u32_e32 v4, 64, v1
	v_xor_b32_e32 v1, 32, v3
	v_cmp_lt_i32_e32 vcc, v1, v4
	v_xor_b32_e32 v5, 16, v3
	s_load_dwordx2 s[2:3], s[0:1], 0x0
	v_cndmask_b32_e32 v1, v3, v1, vcc
	v_cmp_lt_i32_e32 vcc, v5, v4
	s_lshl_b32 s6, s40, 2
	s_ashr_i32 s7, s6, 31
	v_cndmask_b32_e32 v5, v3, v5, vcc
	v_lshlrev_b32_e32 v10, 2, v5
	v_xor_b32_e32 v5, 8, v3
	v_cmp_lt_i32_e32 vcc, v5, v4
	v_cmp_eq_u32_e64 s[0:1], 0, v15
	v_lshlrev_b32_e32 v1, 2, v1
	v_cndmask_b32_e32 v5, v3, v5, vcc
	v_lshlrev_b32_e32 v11, 2, v5
	v_xor_b32_e32 v5, 4, v3
	v_cmp_lt_i32_e32 vcc, v5, v4
	s_lshl_b64 s[8:9], s[6:7], 2
	s_lshl_b64 s[10:11], s[6:7], 11
	v_cndmask_b32_e32 v5, v3, v5, vcc
	v_lshlrev_b32_e32 v12, 2, v5
	v_xor_b32_e32 v5, 2, v3
	v_cmp_lt_i32_e32 vcc, v5, v4
	s_lshl_b64 s[12:13], s[6:7], 12
	s_mov_b64 s[14:15], 0
	v_cndmask_b32_e32 v5, v3, v5, vcc
	v_lshlrev_b32_e32 v13, 2, v5
	v_xor_b32_e32 v5, 1, v3
	v_cmp_lt_i32_e32 vcc, v5, v4
	s_nop 1
	v_cndmask_b32_e32 v3, v3, v5, vcc
	v_lshlrev_b32_e32 v14, 2, v3
	v_ashrrev_i32_e32 v3, 31, v2
	v_lshlrev_b64 v[8:9], 12, v[2:3]
	v_lshl_or_b32 v8, v15, 4, v8
	v_mov_b64_e32 v[4:5], 0x2d700000
	v_lshlrev_b64 v[6:7], 11, v[2:3]
	s_waitcnt lgkmcnt(0)
	v_lshl_add_u64 v[8:9], s[2:3], 0, v[8:9]
	s_mov_b64 s[2:3], 0x800
	v_lshl_add_u64 v[4:5], v[2:3], 2, v[4:5]
	v_lshl_or_b32 v6, v15, 3, v6
	v_lshl_add_u64 v[8:9], v[8:9], 0, s[2:3]
	s_brev_b32 s2, 28
	s_mov_b32 s3, 0xffff
	s_mul_i32 s87, s6, 3
	s_lshl_b32 s88, s6, 2
	s_lshl_b64 s[90:91], s[12:13], 2
	s_lshl_b64 s[92:93], s[10:11], 2
	s_lshl_b64 s[94:95], s[12:13], 1
	s_add_u32 s96, s94, s12
	s_addc_u32 s97, s95, s13
	s_lshl_b64 s[72:73], s[8:9], 2
	s_lshl_b64 s[74:75], s[10:11], 1
	s_add_u32 s76, s74, s10
	s_addc_u32 s77, s75, s11
.Lxprep4_top:
	v_readfirstlane_b32 s86, v2
	s_cmp_gt_i32 s86, s3
	s_cbranch_scc1 .LBB0_88
	s_add_i32 s86, s86, s87
	s_cmp_gt_i32 s86, s3
	s_cbranch_scc1 .LBB0_86
	v_lshl_add_u64 v[52:53], v[8:9], 0, s[12:13]
	v_lshl_add_u64 v[54:55], v[8:9], 0, s[94:95]
	v_lshl_add_u64 v[56:57], v[8:9], 0, s[96:97]
	global_load_dwordx4 v[100:103], v[8:9], off offset:-2048
	global_load_dwordx4 v[104:107], v[8:9], off offset:-1024
	global_load_dwordx4 v[108:111], v[8:9], off
	global_load_dwordx4 v[112:115], v[8:9], off offset:1024
	global_load_dwordx4 v[116:119], v[52:53], off offset:-2048
	global_load_dwordx4 v[120:123], v[52:53], off offset:-1024
	global_load_dwordx4 v[124:127], v[52:53], off
	global_load_dwordx4 v[128:131], v[52:53], off offset:1024
	global_load_dwordx4 v[132:135], v[54:55], off offset:-2048
	global_load_dwordx4 v[136:139], v[54:55], off offset:-1024
	global_load_dwordx4 v[140:143], v[54:55], off
	global_load_dwordx4 v[144:147], v[54:55], off offset:1024
	global_load_dwordx4 v[148:151], v[56:57], off offset:-2048
	global_load_dwordx4 v[152:155], v[56:57], off offset:-1024
	global_load_dwordx4 v[156:159], v[56:57], off
	global_load_dwordx4 v[160:163], v[56:57], off offset:1024
	v_lshl_add_u64 v[58:59], s[18:19], 0, v[6:7]
	v_add_co_u32_e32 v58, vcc, s2, v58
	s_nop 1
	v_addc_co_u32_e32 v59, vcc, 0, v59, vcc
	v_lshl_add_u64 v[60:61], v[58:59], 0, s[10:11]
	v_lshl_add_u64 v[62:63], v[58:59], 0, s[74:75]
	v_lshl_add_u64 v[64:65], v[58:59], 0, s[76:77]
	v_lshl_add_u64 v[66:67], s[18:19], 0, v[4:5]
	s_waitcnt vmcnt(12)
	v_pk_mul_f32 v[32:33], v[100:101], v[100:101]
	v_pk_mul_f32 v[34:35], v[102:103], v[102:103]
	v_pk_mul_f32 v[36:37], v[104:105], v[104:105]
	v_pk_mul_f32 v[38:39], v[106:107], v[106:107]
	v_pk_mul_f32 v[40:41], v[108:109], v[108:109]
	v_pk_mul_f32 v[42:43], v[110:111], v[110:111]
	v_pk_mul_f32 v[44:45], v[112:113], v[112:113]
	v_pk_mul_f32 v[46:47], v[114:115], v[114:115]
	v_add_f32_e32 v48, v32, v33
	v_add_f32_e32 v48, v48, v34
	v_add_f32_e32 v48, v48, v35
	v_add_f32_e32 v49, v36, v37
	v_add_f32_e32 v49, v49, v38
	v_add_f32_e32 v49, v49, v39
	v_add_f32_e32 v50, v40, v41
	v_add_f32_e32 v50, v50, v42
	v_add_f32_e32 v50, v50, v43
	v_add_f32_e32 v51, v44, v45
	v_add_f32_e32 v51, v51, v46
	v_add_f32_e32 v51, v51, v47
	v_add_f32_e32 v3, v48, v49
	v_add_f32_e32 v3, v3, v50
	v_add_f32_e32 v3, v3, v51
	v_cvt_pk_bf16_f32 v100, v100, v101
	v_cvt_pk_bf16_f32 v101, v102, v103
	global_store_dwordx2 v[58:59], v[100:101], off
	v_cvt_pk_bf16_f32 v104, v104, v105
	v_cvt_pk_bf16_f32 v105, v106, v107
	global_store_dwordx2 v[58:59], v[104:105], off offset:512
	v_cvt_pk_bf16_f32 v108, v108, v109
	v_cvt_pk_bf16_f32 v109, v110, v111
	global_store_dwordx2 v[58:59], v[108:109], off offset:1024
	v_cvt_pk_bf16_f32 v112, v112, v113
	v_cvt_pk_bf16_f32 v113, v114, v115
	global_store_dwordx2 v[58:59], v[112:113], off offset:1536
	ds_bpermute_b32 v15, v1, v3
	s_waitcnt lgkmcnt(0)
	v_add_f32_e32 v3, v3, v15
	ds_bpermute_b32 v15, v10, v3
	s_waitcnt lgkmcnt(0)
	v_add_f32_e32 v3, v3, v15
	ds_bpermute_b32 v15, v11, v3
	s_waitcnt lgkmcnt(0)
	v_add_f32_e32 v3, v3, v15
	ds_bpermute_b32 v15, v12, v3
	s_waitcnt lgkmcnt(0)
	v_add_f32_e32 v3, v3, v15
	ds_bpermute_b32 v15, v13, v3
	s_waitcnt lgkmcnt(0)
	v_add_f32_e32 v3, v3, v15
	ds_bpermute_b32 v15, v14, v3
	s_waitcnt lgkmcnt(0)
	v_add_f32_e32 v3, v3, v15
	s_and_saveexec_b64 s[20:21], s[0:1]
	global_store_dword v[66:67], v3, off
	s_or_b64 exec, exec, s[20:21]
	v_lshl_add_u64 v[66:67], v[66:67], 0, s[8:9]
	s_waitcnt vmcnt(13)
	v_pk_mul_f32 v[32:33], v[116:117], v[116:117]
	v_pk_mul_f32 v[34:35], v[118:119], v[118:119]
	v_pk_mul_f32 v[36:37], v[120:121], v[120:121]
	v_pk_mul_f32 v[38:39], v[122:123], v[122:123]
	v_pk_mul_f32 v[40:41], v[124:125], v[124:125]
	v_pk_mul_f32 v[42:43], v[126:127], v[126:127]
	v_pk_mul_f32 v[44:45], v[128:129], v[128:129]
	v_pk_mul_f32 v[46:47], v[130:131], v[130:131]
	v_add_f32_e32 v48, v32, v33
	v_add_f32_e32 v48, v48, v34
	v_add_f32_e32 v48, v48, v35
	v_add_f32_e32 v49, v36, v37
	v_add_f32_e32 v49, v49, v38
	v_add_f32_e32 v49, v49, v39
	v_add_f32_e32 v50, v40, v41
	v_add_f32_e32 v50, v50, v42
	v_add_f32_e32 v50, v50, v43
	v_add_f32_e32 v51, v44, v45
	v_add_f32_e32 v51, v51, v46
	v_add_f32_e32 v51, v51, v47
	v_add_f32_e32 v3, v48, v49
	v_add_f32_e32 v3, v3, v50
	v_add_f32_e32 v3, v3, v51
	v_cvt_pk_bf16_f32 v116, v116, v117
	v_cvt_pk_bf16_f32 v117, v118, v119
	global_store_dwordx2 v[60:61], v[116:117], off
	v_cvt_pk_bf16_f32 v120, v120, v121
	v_cvt_pk_bf16_f32 v121, v122, v123
	global_store_dwordx2 v[60:61], v[120:121], off offset:512
	v_cvt_pk_bf16_f32 v124, v124, v125
	v_cvt_pk_bf16_f32 v125, v126, v127
	global_store_dwordx2 v[60:61], v[124:125], off offset:1024
	v_cvt_pk_bf16_f32 v128, v128, v129
	v_cvt_pk_bf16_f32 v129, v130, v131
	global_store_dwordx2 v[60:61], v[128:129], off offset:1536
	ds_bpermute_b32 v15, v1, v3
	s_waitcnt lgkmcnt(0)
	v_add_f32_e32 v3, v3, v15
	ds_bpermute_b32 v15, v10, v3
	s_waitcnt lgkmcnt(0)
	v_add_f32_e32 v3, v3, v15
	ds_bpermute_b32 v15, v11, v3
	s_waitcnt lgkmcnt(0)
	v_add_f32_e32 v3, v3, v15
	ds_bpermute_b32 v15, v12, v3
	s_waitcnt lgkmcnt(0)
	v_add_f32_e32 v3, v3, v15
	ds_bpermute_b32 v15, v13, v3
	s_waitcnt lgkmcnt(0)
	v_add_f32_e32 v3, v3, v15
	ds_bpermute_b32 v15, v14, v3
	s_waitcnt lgkmcnt(0)
	v_add_f32_e32 v3, v3, v15
	s_and_saveexec_b64 s[20:21], s[0:1]
	global_store_dword v[66:67], v3, off
	s_or_b64 exec, exec, s[20:21]
	v_lshl_add_u64 v[66:67], v[66:67], 0, s[8:9]
	s_waitcnt vmcnt(14)
	v_pk_mul_f32 v[32:33], v[132:133], v[132:133]
	v_pk_mul_f32 v[34:35], v[134:135], v[134:135]
	v_pk_mul_f32 v[36:37], v[136:137], v[136:137]
	v_pk_mul_f32 v[38:39], v[138:139], v[138:139]
	v_pk_mul_f32 v[40:41], v[140:141], v[140:141]
	v_pk_mul_f32 v[42:43], v[142:143], v[142:143]
	v_pk_mul_f32 v[44:45], v[144:145], v[144:145]
	v_pk_mul_f32 v[46:47], v[146:147], v[146:147]
	v_add_f32_e32 v48, v32, v33
	v_add_f32_e32 v48, v48, v34
	v_add_f32_e32 v48, v48, v35
	v_add_f32_e32 v49, v36, v37
	v_add_f32_e32 v49, v49, v38
	v_add_f32_e32 v49, v49, v39
	v_add_f32_e32 v50, v40, v41
	v_add_f32_e32 v50, v50, v42
	v_add_f32_e32 v50, v50, v43
	v_add_f32_e32 v51, v44, v45
	v_add_f32_e32 v51, v51, v46
	v_add_f32_e32 v51, v51, v47
	v_add_f32_e32 v3, v48, v49
	v_add_f32_e32 v3, v3, v50
	v_add_f32_e32 v3, v3, v51
	v_cvt_pk_bf16_f32 v132, v132, v133
	v_cvt_pk_bf16_f32 v133, v134, v135
	global_store_dwordx2 v[62:63], v[132:133], off
	v_cvt_pk_bf16_f32 v136, v136, v137
	v_cvt_pk_bf16_f32 v137, v138, v139
	global_store_dwordx2 v[62:63], v[136:137], off offset:512
	v_cvt_pk_bf16_f32 v140, v140, v141
	v_cvt_pk_bf16_f32 v141, v142, v143
	global_store_dwordx2 v[62:63], v[140:141], off offset:1024
	v_cvt_pk_bf16_f32 v144, v144, v145
	v_cvt_pk_bf16_f32 v145, v146, v147
	global_store_dwordx2 v[62:63], v[144:145], off offset:1536
	ds_bpermute_b32 v15, v1, v3
	s_waitcnt lgkmcnt(0)
	v_add_f32_e32 v3, v3, v15
	ds_bpermute_b32 v15, v10, v3
	s_waitcnt lgkmcnt(0)
	v_add_f32_e32 v3, v3, v15
	ds_bpermute_b32 v15, v11, v3
	s_waitcnt lgkmcnt(0)
	v_add_f32_e32 v3, v3, v15
	ds_bpermute_b32 v15, v12, v3
	s_waitcnt lgkmcnt(0)
	v_add_f32_e32 v3, v3, v15
	ds_bpermute_b32 v15, v13, v3
	s_waitcnt lgkmcnt(0)
	v_add_f32_e32 v3, v3, v15
	ds_bpermute_b32 v15, v14, v3
	s_waitcnt lgkmcnt(0)
	v_add_f32_e32 v3, v3, v15
	s_and_saveexec_b64 s[20:21], s[0:1]
	global_store_dword v[66:67], v3, off
	s_or_b64 exec, exec, s[20:21]
	v_lshl_add_u64 v[66:67], v[66:67], 0, s[8:9]
	s_waitcnt vmcnt(15)
	v_pk_mul_f32 v[32:33], v[148:149], v[148:149]
	v_pk_mul_f32 v[34:35], v[150:151], v[150:151]
	v_pk_mul_f32 v[36:37], v[152:153], v[152:153]
	v_pk_mul_f32 v[38:39], v[154:155], v[154:155]
	v_pk_mul_f32 v[40:41], v[156:157], v[156:157]
	v_pk_mul_f32 v[42:43], v[158:159], v[158:159]
	v_pk_mul_f32 v[44:45], v[160:161], v[160:161]
	v_pk_mul_f32 v[46:47], v[162:163], v[162:163]
	v_add_f32_e32 v48, v32, v33
	v_add_f32_e32 v48, v48, v34
	v_add_f32_e32 v48, v48, v35
	v_add_f32_e32 v49, v36, v37
	v_add_f32_e32 v49, v49, v38
	v_add_f32_e32 v49, v49, v39
	v_add_f32_e32 v50, v40, v41
	v_add_f32_e32 v50, v50, v42
	v_add_f32_e32 v50, v50, v43
	v_add_f32_e32 v51, v44, v45
	v_add_f32_e32 v51, v51, v46
	v_add_f32_e32 v51, v51, v47
	v_add_f32_e32 v3, v48, v49
	v_add_f32_e32 v3, v3, v50
	v_add_f32_e32 v3, v3, v51
	v_cvt_pk_bf16_f32 v148, v148, v149
	v_cvt_pk_bf16_f32 v149, v150, v151
	global_store_dwordx2 v[64:65], v[148:149], off
	v_cvt_pk_bf16_f32 v152, v152, v153
	v_cvt_pk_bf16_f32 v153, v154, v155
	global_store_dwordx2 v[64:65], v[152:153], off offset:512
	v_cvt_pk_bf16_f32 v156, v156, v157
	v_cvt_pk_bf16_f32 v157, v158, v159
	global_store_dwordx2 v[64:65], v[156:157], off offset:1024
	v_cvt_pk_bf16_f32 v160, v160, v161
	v_cvt_pk_bf16_f32 v161, v162, v163
	global_store_dwordx2 v[64:65], v[160:161], off offset:1536
	ds_bpermute_b32 v15, v1, v3
	s_waitcnt lgkmcnt(0)
	v_add_f32_e32 v3, v3, v15
	ds_bpermute_b32 v15, v10, v3
	s_waitcnt lgkmcnt(0)
	v_add_f32_e32 v3, v3, v15
	ds_bpermute_b32 v15, v11, v3
	s_waitcnt lgkmcnt(0)
	v_add_f32_e32 v3, v3, v15
	ds_bpermute_b32 v15, v12, v3
	s_waitcnt lgkmcnt(0)
	v_add_f32_e32 v3, v3, v15
	ds_bpermute_b32 v15, v13, v3
	s_waitcnt lgkmcnt(0)
	v_add_f32_e32 v3, v3, v15
	ds_bpermute_b32 v15, v14, v3
	s_waitcnt lgkmcnt(0)
	v_add_f32_e32 v3, v3, v15
	s_and_saveexec_b64 s[20:21], s[0:1]
	global_store_dword v[66:67], v3, off
	s_or_b64 exec, exec, s[20:21]
	v_add_u32_e32 v2, s88, v2
	v_lshl_add_u64 v[4:5], v[4:5], 0, s[72:73]
	v_lshl_add_u64 v[6:7], v[6:7], 0, s[92:93]
	v_lshl_add_u64 v[8:9], v[8:9], 0, s[90:91]
	s_branch .Lxprep4_top

.LBB0_101:
	s_add_u32 s100, s84, 0x2ce12000
	s_addc_u32 s101, s85, 0
	s_getreg_b32 s98, hwreg(HW_REG_XCC_ID, 0, 4)
	s_lshl_b32 s98, s98, 7
	v_mov_b32_e32 v1, s98
	v_mov_b32_e32 v2, 1
	v_and_b32_e32 v3, 0x3fffffff, v0
	v_cmp_eq_u32_e32 vcc, 0, v3
	s_and_saveexec_b64 s[98:99], vcc
	global_atomic_add v1, v2, s[100:101] offset:-2048
	s_or_b64 exec, exec, s[98:99]
	s_cmp_lt_i32 s38, 2
	s_cselect_b64 s[6:7], -1, 0
	s_and_b64 s[0:1], s[6:7], s[0:1]
	s_andn2_b64 vcc, exec, s[0:1]
	s_cbranch_vccnz .LBB0_228
	s_lshr_b32 s0, s40, 3
	s_and_b32 s1, s82, 7
	s_mul_i32 s0, s0, s1
	s_lshr_b32 s1, s82, 3
	v_and_b32_e32 v1, 0x3ff, v0
	s_add_i32 s2, s0, s1
	s_mov_b64 s[8:9], s[84:85]
	v_mov_b32_e32 v2, v1
	s_cmpk_gt_i32 s2, 0x1cff
	s_cbranch_scc1 .LBB0_228
	v_mov_b32_e32 v3, s8
	v_add_co_u32_e32 v4, vcc, 0x2d500000, v3
	v_mov_b32_e32 v3, s9
	s_nop 0
	v_addc_co_u32_e32 v5, vcc, 0, v3, vcc
	flat_load_dwordx2 v[130:131], v[4:5] offset:288
	s_add_u32 s3, s8, 0x38000000
	s_addc_u32 s63, s9, 0
	v_and_b32_e32 v4, 0xffffff80, v2
	s_add_u32 s50, s8, 0x2d700000
	v_and_b32_e32 v3, 15, v2
	v_and_b32_e32 v6, 64, v2
	v_lshrrev_b32_e32 v7, 2, v2
	v_ashrrev_i32_e32 v5, 31, v4
	s_addc_u32 s51, s9, 0
	v_and_b32_e32 v137, 0xffffff8f, v2
	v_mov_b32_e32 v133, 0
	v_or_b32_e32 v134, v4, v3
	v_and_or_b32 v136, v7, 12, v6
	v_lshlrev_b32_e32 v132, 2, v3
	v_lshl_add_u64 v[2:3], v[4:5], 2, s[50:51]
	v_lshl_add_u64 v[144:145], v[2:3], 0, v[132:133]
	v_lshlrev_b32_e32 v132, 2, v136
	s_mov_b64 s[0:1], 0x4000000
	s_mov_b64 s[4:5], 0x2c000000
	s_add_u32 s52, s8, 0x2d500120
	s_mov_b32 s11, 0
	s_mov_b64 s[12:13], 0x1f000000
	s_movk_i32 s33, 0x1320
	s_mov_b32 s36, 0x13200
	s_mov_b64 s[14:15], 0x20000
	s_mov_b64 s[16:17], 0x40000
	s_mov_b64 s[18:19], 0x60000
	s_movk_i32 s37, 0x4000
	s_mov_b64 s[20:21], 0x20040
	s_mov_b64 s[22:23], 0x40040
	s_mov_b32 s41, 0x8000
	s_mov_b64 s[24:25], 0x60040
	s_mov_b32 s42, 0xc000
	s_mov_b64 s[26:27], 0x38000080
	s_mov_b64 s[28:29], 0x38020080
	s_mov_b64 s[30:31], 0x38040080
	s_mov_b64 s[34:35], 0x38060080
	s_mov_b64 s[44:45], 0x80
	s_mov_b64 s[46:47], 0x20080
	v_mov_b32_e32 v139, 0x358637bd
	s_mov_b32 s43, 0x800000
	s_movk_i32 s62, 0x1c00
	s_mov_b64 s[48:49], 0x1c000
	v_mov_b32_e32 v135, v5
	v_or_b32_e32 v141, 1, v136
	v_or_b32_e32 v143, 2, v136
	v_or_b32_e32 v166, 3, v136
	v_or_b32_e32 v138, 16, v136
	v_or_b32_e32 v140, 32, v136
	v_or_b32_e32 v142, 48, v136
	s_addc_u32 s53, s9, 0
	s_movk_i32 s64, 0x7fff
	s_waitcnt vmcnt(0) lgkmcnt(0)
	v_lshl_add_u64 v[2:3], v[130:131], 0, v[132:133]
	v_lshl_add_u64 v[146:147], v[130:131], 0, s[0:1]
	v_lshl_add_u64 v[148:149], v[2:3], 0, s[4:5]
	s_branch .LBB0_105

.LBB0_228:
	s_cmp_gt_i32 s39, 1
	s_cselect_b64 s[0:1], -1, 0
	s_and_b64 s[2:3], s[6:7], s[0:1]
	s_andn2_b64 vcc, exec, s[2:3]
	s_cbranch_vccnz .LBB0_240
	v_and_b32_e32 v1, 0x3fffffff, v0
	v_cmp_eq_u32_e32 vcc, 0, v1
	s_waitcnt vmcnt(0) lgkmcnt(0)
	s_barrier
	s_and_saveexec_b64 s[4:5], vcc
	s_cbranch_execz .LBB0_239
	s_add_u32 s6, s84, 0x2ce12000
	s_addc_u32 s7, s85, 0
	s_getreg_b32 s98, hwreg(HW_REG_XCC_ID, 0, 4)
	s_lshl_b32 s99, s98, 7
	s_lshl_b32 s98, s98, 8
	v_mov_b32_e32 v1, s98
	v_mov_b32_e32 v3, s99
	v_mov_b32_e32 v4, 0
	s_movk_i32 s101, 0x4000
.Lxb_cen:
	s_mov_b32 s100, 0
	global_load_dword v2, v4, s[6:7] offset:-2048 sc1
	s_waitcnt vmcnt(0)
	v_readfirstlane_b32 s99, v2
	s_add_u32 s100, s100, s99
	global_load_dword v2, v4, s[6:7] offset:-1920 sc1
	s_waitcnt vmcnt(0)
	v_readfirstlane_b32 s99, v2
	s_add_u32 s100, s100, s99
	global_load_dword v2, v4, s[6:7] offset:-1792 sc1
	s_waitcnt vmcnt(0)
	v_readfirstlane_b32 s99, v2
	s_add_u32 s100, s100, s99
	global_load_dword v2, v4, s[6:7] offset:-1664 sc1
	s_waitcnt vmcnt(0)
	v_readfirstlane_b32 s99, v2
	s_add_u32 s100, s100, s99
	global_load_dword v2, v4, s[6:7] offset:-1536 sc1
	s_waitcnt vmcnt(0)
	v_readfirstlane_b32 s99, v2
	s_add_u32 s100, s100, s99
	global_load_dword v2, v4, s[6:7] offset:-1408 sc1
	s_waitcnt vmcnt(0)
	v_readfirstlane_b32 s99, v2
	s_add_u32 s100, s100, s99
	global_load_dword v2, v4, s[6:7] offset:-1280 sc1
	s_waitcnt vmcnt(0)
	v_readfirstlane_b32 s99, v2
	s_add_u32 s100, s100, s99
	global_load_dword v2, v4, s[6:7] offset:-1152 sc1
	s_waitcnt vmcnt(0)
	v_readfirstlane_b32 s99, v2
	s_add_u32 s100, s100, s99
	s_cmp_eq_u32 s100, s40
	s_cbranch_scc1 .Lxb_cen_done
	s_sleep 1
	s_sub_u32 s101, s101, 1
	s_cmp_lg_u32 s101, 0
	s_cbranch_scc1 .Lxb_cen
.Lxb_cen_done:
	v_mov_b32_e32 v2, 1
	global_load_dword v3, v3, s[6:7] offset:-2048 sc1
	global_atomic_add v4, v1, v2, s[6:7] sc0
	s_waitcnt vmcnt(0)
	v_readfirstlane_b32 s100, v3
	v_readfirstlane_b32 s99, v4
	s_mul_i32 s98, s100, 1
	s_add_i32 s99, s99, 1
	s_cmp_lg_u32 s99, s98
	s_cbranch_scc1 .Lxb_follow_1
	buffer_wbl2 sc1
	s_waitcnt vmcnt(0)
	v_mov_b32_e32 v4, 0
	global_atomic_add v2, v4, v3, s[6:7] offset:-4096 sc0
	s_waitcnt vmcnt(0)
	v_readfirstlane_b32 s99, v2
	s_add_i32 s99, s99, s100
	s_mul_i32 s98, s40, 1
	v_mov_b32_e32 v2, 1
	s_cmp_lg_u32 s99, s98
	s_cbranch_scc1 .Lxb_topwait_1
	global_atomic_add v4, v2, s[6:7] offset:-3840
	s_branch .Lxb_topdone_1
.Lxb_topwait_1:
	s_mov_b32 s101, 0x40000
.Lxb_topspin_1:
	global_load_dword v3, v4, s[6:7] offset:-3840 sc1
	s_waitcnt vmcnt(0)
	v_readfirstlane_b32 s99, v3
	s_cmp_ge_u32 s99, 1
	s_cbranch_scc1 .Lxb_topdone_1
	s_sleep 1
	s_sub_u32 s101, s101, 1
	s_cmp_lg_u32 s101, 0
	s_cbranch_scc1 .Lxb_topspin_1
.Lxb_topdone_1:
	buffer_inv sc1
	global_atomic_add v1, v2, s[6:7] offset:128
	s_waitcnt vmcnt(0)
	s_branch .Lxb_end_1

.Lxb_spin_1:
	global_load_dword v3, v1, s[6:7] offset:128 sc1
	s_waitcnt vmcnt(0)
	v_readfirstlane_b32 s99, v3
	s_cmp_ge_u32 s99, 1
	s_cbranch_scc1 .Lxb_rel_1
	s_sleep 1
	s_sub_u32 s101, s101, 1
	s_cmp_lg_u32 s101, 0
	s_cbranch_scc1 .Lxb_spin_1
.Lxb_rel_1:
	buffer_inv sc1
	s_waitcnt vmcnt(0)
.Lxb_end_1:
.LBB0_239:
	s_or_b64 exec, exec, s[4:5]
	s_barrier

.LBB0_383:
	s_cmp_gt_i32 s39, 2
	v_readlane_b32 s2, v247, 0
	s_cselect_b64 s[0:1], -1, 0
	v_readlane_b32 s3, v247, 1
	s_and_b64 s[2:3], s[2:3], s[0:1]
	s_andn2_b64 vcc, exec, s[2:3]
	s_cbranch_vccnz .LBB0_395
	v_and_b32_e32 v1, 0x3fffffff, v0
	v_cmp_eq_u32_e32 vcc, 0, v1
	s_waitcnt vmcnt(0) lgkmcnt(0)
	s_barrier
	s_and_saveexec_b64 s[4:5], vcc
	s_cbranch_execz .LBB0_394
	s_add_u32 s6, s84, 0x2ce12000
	s_addc_u32 s7, s85, 0
	s_getreg_b32 s98, hwreg(HW_REG_XCC_ID, 0, 4)
	s_lshl_b32 s99, s98, 7
	s_lshl_b32 s98, s98, 8
	v_mov_b32_e32 v1, s98
	v_mov_b32_e32 v3, s99
	v_mov_b32_e32 v4, 0
	v_mov_b32_e32 v2, 1
	global_load_dword v3, v3, s[6:7] offset:-2048 sc1
	global_atomic_add v4, v1, v2, s[6:7] sc0
	s_waitcnt vmcnt(0)
	v_readfirstlane_b32 s100, v3
	v_readfirstlane_b32 s99, v4
	s_mul_i32 s98, s100, 2
	s_add_i32 s99, s99, 1
	s_cmp_lg_u32 s99, s98
	s_cbranch_scc1 .Lxb_follow_2
	buffer_wbl2 sc1
	s_waitcnt vmcnt(0)
	v_mov_b32_e32 v4, 0
	global_atomic_add v2, v4, v3, s[6:7] offset:-4096 sc0
	s_waitcnt vmcnt(0)
	v_readfirstlane_b32 s99, v2
	s_add_i32 s99, s99, s100
	s_mul_i32 s98, s40, 2
	v_mov_b32_e32 v2, 1
	s_cmp_lg_u32 s99, s98
	s_cbranch_scc1 .Lxb_topwait_2
	global_atomic_add v4, v2, s[6:7] offset:-3840
	s_branch .Lxb_topdone_2

.Lxb_topspin_2:
	global_load_dword v3, v4, s[6:7] offset:-3840 sc1
	s_waitcnt vmcnt(0)
	v_readfirstlane_b32 s99, v3
	s_cmp_ge_u32 s99, 2
	s_cbranch_scc1 .Lxb_topdone_2
	s_sleep 1
	s_sub_u32 s101, s101, 1
	s_cmp_lg_u32 s101, 0
	s_cbranch_scc1 .Lxb_topspin_2

.Lxb_spin_2:
	global_load_dword v3, v1, s[6:7] offset:128 sc1
	s_waitcnt vmcnt(0)
	v_readfirstlane_b32 s99, v3
	s_cmp_ge_u32 s99, 2
	s_cbranch_scc1 .Lxb_rel_2
	s_sleep 1
	s_sub_u32 s101, s101, 1
	s_cmp_lg_u32 s101, 0
	s_cbranch_scc1 .Lxb_spin_2

.LBB0_494:
	s_cmp_gt_i32 s39, 3
	s_cselect_b64 s[0:1], -1, 0
	s_and_b64 s[2:3], s[12:13], s[0:1]
	s_andn2_b64 vcc, exec, s[2:3]
	s_cbranch_vccnz .LBB0_506
	v_and_b32_e32 v1, 0x3fffffff, v0
	v_cmp_eq_u32_e32 vcc, 0, v1
	s_waitcnt vmcnt(0) lgkmcnt(0)
	s_barrier
	s_and_saveexec_b64 s[4:5], vcc
	s_cbranch_execz .LBB0_505
	s_add_u32 s6, s84, 0x2ce12000
	s_addc_u32 s7, s85, 0
	s_getreg_b32 s98, hwreg(HW_REG_XCC_ID, 0, 4)
	s_lshl_b32 s99, s98, 7
	s_lshl_b32 s98, s98, 8
	v_mov_b32_e32 v1, s98
	v_mov_b32_e32 v3, s99
	v_mov_b32_e32 v4, 0
	v_mov_b32_e32 v2, 1
	global_load_dword v3, v3, s[6:7] offset:-2048 sc1
	global_atomic_add v4, v1, v2, s[6:7] sc0
	s_waitcnt vmcnt(0)
	v_readfirstlane_b32 s100, v3
	v_readfirstlane_b32 s99, v4
	s_mul_i32 s98, s100, 3
	s_add_i32 s99, s99, 1
	s_cmp_lg_u32 s99, s98
	s_cbranch_scc1 .Lxb_follow_3
	buffer_wbl2 sc1
	s_waitcnt vmcnt(0)
	v_mov_b32_e32 v4, 0
	global_atomic_add v2, v4, v3, s[6:7] offset:-4096 sc0
	s_waitcnt vmcnt(0)
	v_readfirstlane_b32 s99, v2
	s_add_i32 s99, s99, s100
	s_mul_i32 s98, s40, 3
	v_mov_b32_e32 v2, 1
	s_cmp_lg_u32 s99, s98
	s_cbranch_scc1 .Lxb_topwait_3
	global_atomic_add v4, v2, s[6:7] offset:-3840
	s_branch .Lxb_topdone_3

.Lxb_topspin_3:
	global_load_dword v3, v4, s[6:7] offset:-3840 sc1
	s_waitcnt vmcnt(0)
	v_readfirstlane_b32 s99, v3
	s_cmp_ge_u32 s99, 3
	s_cbranch_scc1 .Lxb_topdone_3
	s_sleep 1
	s_sub_u32 s101, s101, 1
	s_cmp_lg_u32 s101, 0
	s_cbranch_scc1 .Lxb_topspin_3

.Lxb_spin_3:
	global_load_dword v3, v1, s[6:7] offset:128 sc1
	s_waitcnt vmcnt(0)
	v_readfirstlane_b32 s99, v3
	s_cmp_ge_u32 s99, 3
	s_cbranch_scc1 .Lxb_rel_3
	s_sleep 1
	s_sub_u32 s101, s101, 1
	s_cmp_lg_u32 s101, 0
	s_cbranch_scc1 .Lxb_spin_3

.LBB0_514:
	s_cmp_gt_i32 s39, 4
	s_cselect_b64 s[0:1], -1, 0
	s_and_b64 s[2:3], s[16:17], s[0:1]
	s_andn2_b64 vcc, exec, s[2:3]
	s_cbranch_vccnz .LBB0_526
	v_and_b32_e32 v1, 0x3fffffff, v0
	v_cmp_eq_u32_e32 vcc, 0, v1
	s_waitcnt vmcnt(0) lgkmcnt(0)
	s_barrier
	s_and_saveexec_b64 s[4:5], vcc
	s_cbranch_execz .LBB0_525
	s_add_u32 s6, s84, 0x2ce12000
	s_addc_u32 s7, s85, 0
	s_getreg_b32 s98, hwreg(HW_REG_XCC_ID, 0, 4)
	s_lshl_b32 s99, s98, 7
	s_lshl_b32 s98, s98, 8
	v_mov_b32_e32 v1, s98
	v_mov_b32_e32 v3, s99
	v_mov_b32_e32 v4, 0
	v_mov_b32_e32 v2, 1
	global_load_dword v3, v3, s[6:7] offset:-2048 sc1
	global_atomic_add v4, v1, v2, s[6:7] sc0
	s_waitcnt vmcnt(0)
	v_readfirstlane_b32 s100, v3
	v_readfirstlane_b32 s99, v4
	s_mul_i32 s98, s100, 4
	s_add_i32 s99, s99, 1
	s_cmp_lg_u32 s99, s98
	s_cbranch_scc1 .Lxb_follow_4
	buffer_wbl2 sc1
	s_waitcnt vmcnt(0)
	v_mov_b32_e32 v4, 0
	global_atomic_add v2, v4, v3, s[6:7] offset:-4096 sc0
	s_waitcnt vmcnt(0)
	v_readfirstlane_b32 s99, v2
	s_add_i32 s99, s99, s100
	s_mul_i32 s98, s40, 4
	v_mov_b32_e32 v2, 1
	s_cmp_lg_u32 s99, s98
	s_cbranch_scc1 .Lxb_topwait_4
	global_atomic_add v4, v2, s[6:7] offset:-3840
	s_branch .Lxb_topdone_4

.Lxb_topspin_4:
	global_load_dword v3, v4, s[6:7] offset:-3840 sc1
	s_waitcnt vmcnt(0)
	v_readfirstlane_b32 s99, v3
	s_cmp_ge_u32 s99, 4
	s_cbranch_scc1 .Lxb_topdone_4
	s_sleep 1
	s_sub_u32 s101, s101, 1
	s_cmp_lg_u32 s101, 0
	s_cbranch_scc1 .Lxb_topspin_4

.Lxb_spin_4:
	global_load_dword v3, v1, s[6:7] offset:128 sc1
	s_waitcnt vmcnt(0)
	v_readfirstlane_b32 s99, v3
	s_cmp_ge_u32 s99, 4
	s_cbranch_scc1 .Lxb_rel_4
	s_sleep 1
	s_sub_u32 s101, s101, 1
	s_cmp_lg_u32 s101, 0
	s_cbranch_scc1 .Lxb_spin_4

.LBB0_548:
	s_cmp_gt_i32 s39, 5
	s_cselect_b64 s[6:7], -1, 0
	s_and_b64 s[0:1], s[4:5], s[6:7]
	s_andn2_b64 vcc, exec, s[0:1]
	s_cbranch_vccnz .LBB0_560
	v_and_b32_e32 v1, 0x3fffffff, v0
	v_cmp_eq_u32_e32 vcc, 0, v1
	s_waitcnt vmcnt(0) lgkmcnt(0)
	s_barrier
	s_and_saveexec_b64 s[0:1], vcc
	s_cbranch_execz .LBB0_559
	s_add_u32 s4, s84, 0x2ce12000
	s_addc_u32 s5, s85, 0
	s_getreg_b32 s98, hwreg(HW_REG_XCC_ID, 0, 4)
	s_lshl_b32 s99, s98, 7
	s_lshl_b32 s98, s98, 8
	v_mov_b32_e32 v1, s98
	v_mov_b32_e32 v3, s99
	v_mov_b32_e32 v4, 0
	v_mov_b32_e32 v2, 1
	global_load_dword v3, v3, s[4:5] offset:-2048 sc1
	global_atomic_add v4, v1, v2, s[4:5] sc0
	s_waitcnt vmcnt(0)
	v_readfirstlane_b32 s100, v3
	v_readfirstlane_b32 s99, v4
	s_mul_i32 s98, s100, 5
	s_add_i32 s99, s99, 1
	s_cmp_lg_u32 s99, s98
	s_cbranch_scc1 .Lxb_follow_5
	buffer_wbl2 sc1
	s_waitcnt vmcnt(0)
	v_mov_b32_e32 v4, 0
	global_atomic_add v2, v4, v3, s[4:5] offset:-4096 sc0
	s_waitcnt vmcnt(0)
	v_readfirstlane_b32 s99, v2
	s_add_i32 s99, s99, s100
	s_mul_i32 s98, s40, 5
	v_mov_b32_e32 v2, 1
	s_cmp_lg_u32 s99, s98
	s_cbranch_scc1 .Lxb_topwait_5
	global_atomic_add v4, v2, s[4:5] offset:-3840
	s_branch .Lxb_topdone_5

.Lxb_topspin_5:
	global_load_dword v3, v4, s[4:5] offset:-3840 sc1
	s_waitcnt vmcnt(0)
	v_readfirstlane_b32 s99, v3
	s_cmp_ge_u32 s99, 5
	s_cbranch_scc1 .Lxb_topdone_5
	s_sleep 1
	s_sub_u32 s101, s101, 1
	s_cmp_lg_u32 s101, 0
	s_cbranch_scc1 .Lxb_topspin_5
.Lxb_topdone_5:
	buffer_inv sc1
	global_atomic_add v1, v2, s[4:5] offset:128
	s_waitcnt vmcnt(0)
	s_branch .Lxb_end_5

.Lxb_spin_5:
	global_load_dword v3, v1, s[4:5] offset:128 sc1
	s_waitcnt vmcnt(0)
	v_readfirstlane_b32 s99, v3
	s_cmp_ge_u32 s99, 5
	s_cbranch_scc1 .Lxb_rel_5
	s_sleep 1
	s_sub_u32 s101, s101, 1
	s_cmp_lg_u32 s101, 0
	s_cbranch_scc1 .Lxb_spin_5

.Lxb_end_5:
.LBB0_559:
	s_or_b64 exec, exec, s[0:1]
	s_barrier

.LBB0_570:
	s_cmp_gt_i32 s39, 6
	s_cselect_b64 s[6:7], -1, 0
	s_and_b64 s[0:1], s[0:1], s[6:7]
	s_andn2_b64 vcc, exec, s[0:1]
	s_cbranch_vccnz .LBB0_582
	v_and_b32_e32 v1, 0x3fffffff, v0
	v_cmp_eq_u32_e32 vcc, 0, v1
	s_waitcnt vmcnt(0) lgkmcnt(0)
	s_barrier
	s_and_saveexec_b64 s[0:1], vcc
	s_cbranch_execz .LBB0_581
	s_add_u32 s4, s84, 0x2ce12000
	s_addc_u32 s5, s85, 0
	s_getreg_b32 s98, hwreg(HW_REG_XCC_ID, 0, 4)
	s_lshl_b32 s99, s98, 7
	s_lshl_b32 s98, s98, 8
	v_mov_b32_e32 v1, s98
	v_mov_b32_e32 v3, s99
	v_mov_b32_e32 v4, 0
	v_mov_b32_e32 v2, 1
	global_load_dword v3, v3, s[4:5] offset:-2048 sc1
	global_atomic_add v4, v1, v2, s[4:5] sc0
	s_waitcnt vmcnt(0)
	v_readfirstlane_b32 s100, v3
	v_readfirstlane_b32 s99, v4
	s_mul_i32 s98, s100, 6
	s_add_i32 s99, s99, 1
	s_cmp_lg_u32 s99, s98
	s_cbranch_scc1 .Lxb_follow_6
	buffer_wbl2 sc1
	s_waitcnt vmcnt(0)
	v_mov_b32_e32 v4, 0
	global_atomic_add v2, v4, v3, s[4:5] offset:-4096 sc0
	s_waitcnt vmcnt(0)
	v_readfirstlane_b32 s99, v2
	s_add_i32 s99, s99, s100
	s_mul_i32 s98, s40, 6
	v_mov_b32_e32 v2, 1
	s_cmp_lg_u32 s99, s98
	s_cbranch_scc1 .Lxb_topwait_6
	global_atomic_add v4, v2, s[4:5] offset:-3840
	s_branch .Lxb_topdone_6

.Lxb_topspin_6:
	global_load_dword v3, v4, s[4:5] offset:-3840 sc1
	s_waitcnt vmcnt(0)
	v_readfirstlane_b32 s99, v3
	s_cmp_ge_u32 s99, 6
	s_cbranch_scc1 .Lxb_topdone_6
	s_sleep 1
	s_sub_u32 s101, s101, 1
	s_cmp_lg_u32 s101, 0
	s_cbranch_scc1 .Lxb_topspin_6

.Lxb_spin_6:
	global_load_dword v3, v1, s[4:5] offset:128 sc1
	s_waitcnt vmcnt(0)
	v_readfirstlane_b32 s99, v3
	s_cmp_ge_u32 s99, 6
	s_cbranch_scc1 .Lxb_rel_6
	s_sleep 1
	s_sub_u32 s101, s101, 1
	s_cmp_lg_u32 s101, 0
	s_cbranch_scc1 .Lxb_spin_6

.LBB0_604:
	s_cmp_gt_i32 s39, 7
	s_cselect_b64 s[0:1], -1, 0
	s_and_b64 s[2:3], s[4:5], s[0:1]
	s_andn2_b64 vcc, exec, s[2:3]
	s_cbranch_vccnz .LBB0_616
	v_and_b32_e32 v1, 0x3fffffff, v0
	v_cmp_eq_u32_e32 vcc, 0, v1
	s_waitcnt vmcnt(0) lgkmcnt(0)
	s_barrier
	s_and_saveexec_b64 s[4:5], vcc
	s_cbranch_execz .LBB0_615
	s_add_u32 s6, s84, 0x2ce12000
	s_addc_u32 s7, s85, 0
	s_getreg_b32 s98, hwreg(HW_REG_XCC_ID, 0, 4)
	s_lshl_b32 s99, s98, 7
	s_lshl_b32 s98, s98, 8
	v_mov_b32_e32 v1, s98
	v_mov_b32_e32 v3, s99
	v_mov_b32_e32 v4, 0
	v_mov_b32_e32 v2, 1
	global_load_dword v3, v3, s[6:7] offset:-2048 sc1
	global_atomic_add v4, v1, v2, s[6:7] sc0
	s_waitcnt vmcnt(0)
	v_readfirstlane_b32 s100, v3
	v_readfirstlane_b32 s99, v4
	s_mul_i32 s98, s100, 7
	s_add_i32 s99, s99, 1
	s_cmp_lg_u32 s99, s98
	s_cbranch_scc1 .Lxb_follow_7
	buffer_wbl2 sc1
	s_waitcnt vmcnt(0)
	v_mov_b32_e32 v4, 0
	global_atomic_add v2, v4, v3, s[6:7] offset:-4096 sc0
	s_waitcnt vmcnt(0)
	v_readfirstlane_b32 s99, v2
	s_add_i32 s99, s99, s100
	s_mul_i32 s98, s40, 7
	v_mov_b32_e32 v2, 1
	s_cmp_lg_u32 s99, s98
	s_cbranch_scc1 .Lxb_topwait_7
	global_atomic_add v4, v2, s[6:7] offset:-3840
	s_branch .Lxb_topdone_7

.Lxb_topspin_7:
	global_load_dword v3, v4, s[6:7] offset:-3840 sc1
	s_waitcnt vmcnt(0)
	v_readfirstlane_b32 s99, v3
	s_cmp_ge_u32 s99, 7
	s_cbranch_scc1 .Lxb_topdone_7
	s_sleep 1
	s_sub_u32 s101, s101, 1
	s_cmp_lg_u32 s101, 0
	s_cbranch_scc1 .Lxb_topspin_7

.Lxb_spin_7:
	global_load_dword v3, v1, s[6:7] offset:128 sc1
	s_waitcnt vmcnt(0)
	v_readfirstlane_b32 s99, v3
	s_cmp_ge_u32 s99, 7
	s_cbranch_scc1 .Lxb_rel_7
	s_sleep 1
	s_sub_u32 s101, s101, 1
	s_cmp_lg_u32 s101, 0
	s_cbranch_scc1 .Lxb_spin_7

.LBB0_638:
	s_cmp_gt_i32 s39, 8
	s_cselect_b64 s[0:1], -1, 0
	s_and_b64 s[2:3], s[10:11], s[0:1]
	s_andn2_b64 vcc, exec, s[2:3]
	s_cbranch_vccnz .LBB0_650
	v_and_b32_e32 v1, 0x3fffffff, v0
	v_cmp_eq_u32_e32 vcc, 0, v1
	s_waitcnt vmcnt(0) lgkmcnt(0)
	s_barrier
	s_and_saveexec_b64 s[4:5], vcc
	s_cbranch_execz .LBB0_649
	s_add_u32 s6, s84, 0x2ce12000
	s_addc_u32 s7, s85, 0
	s_getreg_b32 s98, hwreg(HW_REG_XCC_ID, 0, 4)
	s_lshl_b32 s99, s98, 7
	s_lshl_b32 s98, s98, 8
	v_mov_b32_e32 v1, s98
	v_mov_b32_e32 v3, s99
	v_mov_b32_e32 v4, 0
	v_mov_b32_e32 v2, 1
	global_load_dword v3, v3, s[6:7] offset:-2048 sc1
	global_atomic_add v4, v1, v2, s[6:7] sc0
	s_waitcnt vmcnt(0)
	v_readfirstlane_b32 s100, v3
	v_readfirstlane_b32 s99, v4
	s_mul_i32 s98, s100, 8
	s_add_i32 s99, s99, 1
	s_cmp_lg_u32 s99, s98
	s_cbranch_scc1 .Lxb_follow_8
	buffer_wbl2 sc1
	s_waitcnt vmcnt(0)
	v_mov_b32_e32 v4, 0
	global_atomic_add v2, v4, v3, s[6:7] offset:-4096 sc0
	s_waitcnt vmcnt(0)
	v_readfirstlane_b32 s99, v2
	s_add_i32 s99, s99, s100
	s_mul_i32 s98, s40, 8
	v_mov_b32_e32 v2, 1
	s_cmp_lg_u32 s99, s98
	s_cbranch_scc1 .Lxb_topwait_8
	global_atomic_add v4, v2, s[6:7] offset:-3840
	s_branch .Lxb_topdone_8

.Lxb_topspin_8:
	global_load_dword v3, v4, s[6:7] offset:-3840 sc1
	s_waitcnt vmcnt(0)
	v_readfirstlane_b32 s99, v3
	s_cmp_ge_u32 s99, 8
	s_cbranch_scc1 .Lxb_topdone_8
	s_sleep 1
	s_sub_u32 s101, s101, 1
	s_cmp_lg_u32 s101, 0
	s_cbranch_scc1 .Lxb_topspin_8

.Lxb_spin_8:
	global_load_dword v3, v1, s[6:7] offset:128 sc1
	s_waitcnt vmcnt(0)
	v_readfirstlane_b32 s99, v3
	s_cmp_ge_u32 s99, 8
	s_cbranch_scc1 .Lxb_rel_8
	s_sleep 1
	s_sub_u32 s101, s101, 1
	s_cmp_lg_u32 s101, 0
	s_cbranch_scc1 .Lxb_spin_8

.LBB0_905:
	s_cmp_gt_i32 s39, 9
	s_cselect_b64 s[0:1], -1, 0
	s_and_b64 s[2:3], s[10:11], s[0:1]
	s_andn2_b64 vcc, exec, s[2:3]
	s_cbranch_vccnz .LBB0_917
	v_and_b32_e32 v1, 0x3fffffff, v0
	v_cmp_eq_u32_e32 vcc, 0, v1
	s_waitcnt vmcnt(0) lgkmcnt(0)
	s_barrier
	s_and_saveexec_b64 s[4:5], vcc
	s_cbranch_execz .LBB0_916
	s_add_u32 s6, s84, 0x2ce12000
	s_addc_u32 s7, s85, 0
	s_getreg_b32 s98, hwreg(HW_REG_XCC_ID, 0, 4)
	s_lshl_b32 s99, s98, 7
	s_lshl_b32 s98, s98, 8
	v_mov_b32_e32 v1, s98
	v_mov_b32_e32 v3, s99
	v_mov_b32_e32 v4, 0
	v_mov_b32_e32 v2, 1
	global_load_dword v3, v3, s[6:7] offset:-2048 sc1
	global_atomic_add v4, v1, v2, s[6:7] sc0
	s_waitcnt vmcnt(0)
	v_readfirstlane_b32 s100, v3
	v_readfirstlane_b32 s99, v4
	s_mul_i32 s98, s100, 9
	s_add_i32 s99, s99, 1
	s_cmp_lg_u32 s99, s98
	s_cbranch_scc1 .Lxb_follow_9
	buffer_wbl2 sc1
	s_waitcnt vmcnt(0)
	v_mov_b32_e32 v4, 0
	global_atomic_add v2, v4, v3, s[6:7] offset:-4096 sc0
	s_waitcnt vmcnt(0)
	v_readfirstlane_b32 s99, v2
	s_add_i32 s99, s99, s100
	s_mul_i32 s98, s40, 9
	v_mov_b32_e32 v2, 1
	s_cmp_lg_u32 s99, s98
	s_cbranch_scc1 .Lxb_topwait_9
	global_atomic_add v4, v2, s[6:7] offset:-3840
	s_branch .Lxb_topdone_9

.Lxb_topspin_9:
	global_load_dword v3, v4, s[6:7] offset:-3840 sc1
	s_waitcnt vmcnt(0)
	v_readfirstlane_b32 s99, v3
	s_cmp_ge_u32 s99, 9
	s_cbranch_scc1 .Lxb_topdone_9
	s_sleep 1
	s_sub_u32 s101, s101, 1
	s_cmp_lg_u32 s101, 0
	s_cbranch_scc1 .Lxb_topspin_9

.Lxb_spin_9:
	global_load_dword v3, v1, s[6:7] offset:128 sc1
	s_waitcnt vmcnt(0)
	v_readfirstlane_b32 s99, v3
	s_cmp_ge_u32 s99, 9
	s_cbranch_scc1 .Lxb_rel_9
	s_sleep 1
	s_sub_u32 s101, s101, 1
	s_cmp_lg_u32 s101, 0
	s_cbranch_scc1 .Lxb_spin_9

.LBB0_1087:
	s_cmp_gt_i32 s39, 10
	s_cselect_b64 s[0:1], -1, 0
	s_and_b64 s[2:3], s[4:5], s[0:1]
	s_andn2_b64 vcc, exec, s[2:3]
	s_cbranch_vccnz .LBB0_1099
	v_and_b32_e32 v1, 0x3fffffff, v0
	v_cmp_eq_u32_e32 vcc, 0, v1
	s_waitcnt vmcnt(0) lgkmcnt(0)
	s_barrier
	s_and_saveexec_b64 s[4:5], vcc
	s_cbranch_execz .LBB0_1098
	s_add_u32 s6, s84, 0x2ce12000
	s_addc_u32 s7, s85, 0
	s_getreg_b32 s98, hwreg(HW_REG_XCC_ID, 0, 4)
	s_lshl_b32 s99, s98, 7
	s_lshl_b32 s98, s98, 8
	v_mov_b32_e32 v1, s98
	v_mov_b32_e32 v3, s99
	v_mov_b32_e32 v4, 0
	v_mov_b32_e32 v2, 1
	global_load_dword v3, v3, s[6:7] offset:-2048 sc1
	global_atomic_add v4, v1, v2, s[6:7] sc0
	s_waitcnt vmcnt(0)
	v_readfirstlane_b32 s100, v3
	v_readfirstlane_b32 s99, v4
	s_mul_i32 s98, s100, 10
	s_add_i32 s99, s99, 1
	s_cmp_lg_u32 s99, s98
	s_cbranch_scc1 .Lxb_follow_10
	buffer_wbl2 sc1
	s_waitcnt vmcnt(0)
	v_mov_b32_e32 v4, 0
	global_atomic_add v2, v4, v3, s[6:7] offset:-4096 sc0
	s_waitcnt vmcnt(0)
	v_readfirstlane_b32 s99, v2
	s_add_i32 s99, s99, s100
	s_mul_i32 s98, s40, 10
	v_mov_b32_e32 v2, 1
	s_cmp_lg_u32 s99, s98
	s_cbranch_scc1 .Lxb_topwait_10
	global_atomic_add v4, v2, s[6:7] offset:-3840
	s_branch .Lxb_topdone_10

.Lxb_topspin_10:
	global_load_dword v3, v4, s[6:7] offset:-3840 sc1
	s_waitcnt vmcnt(0)
	v_readfirstlane_b32 s99, v3
	s_cmp_ge_u32 s99, 10
	s_cbranch_scc1 .Lxb_topdone_10
	s_sleep 1
	s_sub_u32 s101, s101, 1
	s_cmp_lg_u32 s101, 0
	s_cbranch_scc1 .Lxb_topspin_10

.Lxb_spin_10:
	global_load_dword v3, v1, s[6:7] offset:128 sc1
	s_waitcnt vmcnt(0)
	v_readfirstlane_b32 s99, v3
	s_cmp_ge_u32 s99, 10
	s_cbranch_scc1 .Lxb_rel_10
	s_sleep 1
	s_sub_u32 s101, s101, 1
	s_cmp_lg_u32 s101, 0
	s_cbranch_scc1 .Lxb_spin_10

.LBB0_1339:
	s_cmp_gt_i32 s39, 11
	s_cselect_b64 s[0:1], -1, 0
	s_and_b64 s[2:3], s[2:3], s[0:1]
	s_andn2_b64 vcc, exec, s[2:3]
	s_cbranch_vccnz .LBB0_1351
	v_and_b32_e32 v1, 0x3fffffff, v0
	v_cmp_eq_u32_e32 vcc, 0, v1
	s_waitcnt vmcnt(0) lgkmcnt(0)
	s_barrier
	s_and_saveexec_b64 s[4:5], vcc
	s_cbranch_execz .LBB0_1350
	s_add_u32 s6, s84, 0x2ce12000
	s_addc_u32 s7, s85, 0
	s_getreg_b32 s98, hwreg(HW_REG_XCC_ID, 0, 4)
	s_lshl_b32 s99, s98, 7
	s_lshl_b32 s98, s98, 8
	v_mov_b32_e32 v1, s98
	v_mov_b32_e32 v3, s99
	v_mov_b32_e32 v4, 0
	v_mov_b32_e32 v2, 1
	global_load_dword v3, v3, s[6:7] offset:-2048 sc1
	global_atomic_add v4, v1, v2, s[6:7] sc0
	s_waitcnt vmcnt(0)
	v_readfirstlane_b32 s100, v3
	v_readfirstlane_b32 s99, v4
	s_mul_i32 s98, s100, 11
	s_add_i32 s99, s99, 1
	s_cmp_lg_u32 s99, s98
	s_cbranch_scc1 .Lxb_follow_11
	buffer_wbl2 sc1
	s_waitcnt vmcnt(0)
	v_mov_b32_e32 v4, 0
	global_atomic_add v2, v4, v3, s[6:7] offset:-4096 sc0
	s_waitcnt vmcnt(0)
	v_readfirstlane_b32 s99, v2
	s_add_i32 s99, s99, s100
	s_mul_i32 s98, s40, 11
	v_mov_b32_e32 v2, 1
	s_cmp_lg_u32 s99, s98
	s_cbranch_scc1 .Lxb_topwait_11
	global_atomic_add v4, v2, s[6:7] offset:-3840
	s_branch .Lxb_topdone_11

.Lxb_topspin_11:
	global_load_dword v3, v4, s[6:7] offset:-3840 sc1
	s_waitcnt vmcnt(0)
	v_readfirstlane_b32 s99, v3
	s_cmp_ge_u32 s99, 11
	s_cbranch_scc1 .Lxb_topdone_11
	s_sleep 1
	s_sub_u32 s101, s101, 1
	s_cmp_lg_u32 s101, 0
	s_cbranch_scc1 .Lxb_topspin_11

.Lxb_spin_11:
	global_load_dword v3, v1, s[6:7] offset:128 sc1
	s_waitcnt vmcnt(0)
	v_readfirstlane_b32 s99, v3
	s_cmp_ge_u32 s99, 11
	s_cbranch_scc1 .Lxb_rel_11
	s_sleep 1
	s_sub_u32 s101, s101, 1
	s_cmp_lg_u32 s101, 0
	s_cbranch_scc1 .Lxb_spin_11

.LBB0_1373:
	s_cmp_gt_i32 s39, 12
	s_cselect_b64 s[6:7], -1, 0
	s_and_b64 s[0:1], s[4:5], s[6:7]
	s_andn2_b64 vcc, exec, s[0:1]
	s_cbranch_vccnz .LBB0_1385
	v_and_b32_e32 v1, 0x3fffffff, v0
	v_cmp_eq_u32_e32 vcc, 0, v1
	s_waitcnt vmcnt(0) lgkmcnt(0)
	s_barrier
	s_and_saveexec_b64 s[0:1], vcc
	s_cbranch_execz .LBB0_1384
	s_add_u32 s4, s84, 0x2ce12000
	s_addc_u32 s5, s85, 0
	s_getreg_b32 s98, hwreg(HW_REG_XCC_ID, 0, 4)
	s_lshl_b32 s99, s98, 7
	s_lshl_b32 s98, s98, 8
	v_mov_b32_e32 v1, s98
	v_mov_b32_e32 v3, s99
	v_mov_b32_e32 v4, 0
	v_mov_b32_e32 v2, 1
	global_load_dword v3, v3, s[4:5] offset:-2048 sc1
	global_atomic_add v4, v1, v2, s[4:5] sc0
	s_waitcnt vmcnt(0)
	v_readfirstlane_b32 s100, v3
	v_readfirstlane_b32 s99, v4
	s_mul_i32 s98, s100, 12
	s_add_i32 s99, s99, 1
	s_cmp_lg_u32 s99, s98
	s_cbranch_scc1 .Lxb_follow_12
	buffer_wbl2 sc1
	s_waitcnt vmcnt(0)
	v_mov_b32_e32 v4, 0
	global_atomic_add v2, v4, v3, s[4:5] offset:-4096 sc0
	s_waitcnt vmcnt(0)
	v_readfirstlane_b32 s99, v2
	s_add_i32 s99, s99, s100
	s_mul_i32 s98, s40, 12
	v_mov_b32_e32 v2, 1
	s_cmp_lg_u32 s99, s98
	s_cbranch_scc1 .Lxb_topwait_12
	global_atomic_add v4, v2, s[4:5] offset:-3840
	s_branch .Lxb_topdone_12

.Lxb_topspin_12:
	global_load_dword v3, v4, s[4:5] offset:-3840 sc1
	s_waitcnt vmcnt(0)
	v_readfirstlane_b32 s99, v3
	s_cmp_ge_u32 s99, 12
	s_cbranch_scc1 .Lxb_topdone_12
	s_sleep 1
	s_sub_u32 s101, s101, 1
	s_cmp_lg_u32 s101, 0
	s_cbranch_scc1 .Lxb_topspin_12

.Lxb_spin_12:
	global_load_dword v3, v1, s[4:5] offset:128 sc1
	s_waitcnt vmcnt(0)
	v_readfirstlane_b32 s99, v3
	s_cmp_ge_u32 s99, 12
	s_cbranch_scc1 .Lxb_rel_12
	s_sleep 1
	s_sub_u32 s101, s101, 1
	s_cmp_lg_u32 s101, 0
	s_cbranch_scc1 .Lxb_spin_12

.LBB0_1395:
	s_cmp_gt_i32 s39, 13
	s_cselect_b64 s[6:7], -1, 0
	s_and_b64 s[0:1], s[0:1], s[6:7]
	s_andn2_b64 vcc, exec, s[0:1]
	s_cbranch_vccnz .LBB0_1407
	v_and_b32_e32 v1, 0x3fffffff, v0
	v_cmp_eq_u32_e32 vcc, 0, v1
	s_waitcnt vmcnt(0) lgkmcnt(0)
	s_barrier
	s_and_saveexec_b64 s[0:1], vcc
	s_cbranch_execz .LBB0_1406
	s_add_u32 s4, s84, 0x2ce12000
	s_addc_u32 s5, s85, 0
	s_getreg_b32 s98, hwreg(HW_REG_XCC_ID, 0, 4)
	s_lshl_b32 s99, s98, 7
	s_lshl_b32 s98, s98, 8
	v_mov_b32_e32 v1, s98
	v_mov_b32_e32 v3, s99
	v_mov_b32_e32 v4, 0
	v_mov_b32_e32 v2, 1
	global_load_dword v3, v3, s[4:5] offset:-2048 sc1
	global_atomic_add v4, v1, v2, s[4:5] sc0
	s_waitcnt vmcnt(0)
	v_readfirstlane_b32 s100, v3
	v_readfirstlane_b32 s99, v4
	s_mul_i32 s98, s100, 13
	s_add_i32 s99, s99, 1
	s_cmp_lg_u32 s99, s98
	s_cbranch_scc1 .Lxb_follow_13
	buffer_wbl2 sc1
	s_waitcnt vmcnt(0)
	v_mov_b32_e32 v4, 0
	global_atomic_add v2, v4, v3, s[4:5] offset:-4096 sc0
	s_waitcnt vmcnt(0)
	v_readfirstlane_b32 s99, v2
	s_add_i32 s99, s99, s100
	s_mul_i32 s98, s40, 13
	v_mov_b32_e32 v2, 1
	s_cmp_lg_u32 s99, s98
	s_cbranch_scc1 .Lxb_topwait_13
	global_atomic_add v4, v2, s[4:5] offset:-3840
	s_branch .Lxb_topdone_13

.Lxb_topspin_13:
	global_load_dword v3, v4, s[4:5] offset:-3840 sc1
	s_waitcnt vmcnt(0)
	v_readfirstlane_b32 s99, v3
	s_cmp_ge_u32 s99, 13
	s_cbranch_scc1 .Lxb_topdone_13
	s_sleep 1
	s_sub_u32 s101, s101, 1
	s_cmp_lg_u32 s101, 0
	s_cbranch_scc1 .Lxb_topspin_13

.Lxb_spin_13:
	global_load_dword v3, v1, s[4:5] offset:128 sc1
	s_waitcnt vmcnt(0)
	v_readfirstlane_b32 s99, v3
	s_cmp_ge_u32 s99, 13
	s_cbranch_scc1 .Lxb_rel_13
	s_sleep 1
	s_sub_u32 s101, s101, 1
	s_cmp_lg_u32 s101, 0
	s_cbranch_scc1 .Lxb_spin_13

.LBB0_1429:
	s_cmp_gt_i32 s39, 14
	s_cselect_b64 s[0:1], -1, 0
	s_and_b64 s[2:3], s[4:5], s[0:1]
	s_andn2_b64 vcc, exec, s[2:3]
	s_cbranch_vccnz .LBB0_1441
	v_and_b32_e32 v1, 0x3fffffff, v0
	v_cmp_eq_u32_e32 vcc, 0, v1
	s_waitcnt vmcnt(0) lgkmcnt(0)
	s_barrier
	s_and_saveexec_b64 s[4:5], vcc
	s_cbranch_execz .LBB0_1440
	s_add_u32 s6, s84, 0x2ce12000
	s_addc_u32 s7, s85, 0
	s_getreg_b32 s98, hwreg(HW_REG_XCC_ID, 0, 4)
	s_lshl_b32 s99, s98, 7
	s_lshl_b32 s98, s98, 8
	v_mov_b32_e32 v1, s98
	v_mov_b32_e32 v3, s99
	v_mov_b32_e32 v4, 0
	v_mov_b32_e32 v2, 1
	global_load_dword v3, v3, s[6:7] offset:-2048 sc1
	global_atomic_add v4, v1, v2, s[6:7] sc0
	s_waitcnt vmcnt(0)
	v_readfirstlane_b32 s100, v3
	v_readfirstlane_b32 s99, v4
	s_mul_i32 s98, s100, 14
	s_add_i32 s99, s99, 1
	s_cmp_lg_u32 s99, s98
	s_cbranch_scc1 .Lxb_follow_14
	buffer_wbl2 sc1
	s_waitcnt vmcnt(0)
	v_mov_b32_e32 v4, 0
	global_atomic_add v2, v4, v3, s[6:7] offset:-4096 sc0
	s_waitcnt vmcnt(0)
	v_readfirstlane_b32 s99, v2
	s_add_i32 s99, s99, s100
	s_mul_i32 s98, s40, 14
	v_mov_b32_e32 v2, 1
	s_cmp_lg_u32 s99, s98
	s_cbranch_scc1 .Lxb_topwait_14
	global_atomic_add v4, v2, s[6:7] offset:-3840
	s_branch .Lxb_topdone_14

.Lxb_topspin_14:
	global_load_dword v3, v4, s[6:7] offset:-3840 sc1
	s_waitcnt vmcnt(0)
	v_readfirstlane_b32 s99, v3
	s_cmp_ge_u32 s99, 14
	s_cbranch_scc1 .Lxb_topdone_14
	s_sleep 1
	s_sub_u32 s101, s101, 1
	s_cmp_lg_u32 s101, 0
	s_cbranch_scc1 .Lxb_topspin_14

.Lxb_spin_14:
	global_load_dword v3, v1, s[6:7] offset:128 sc1
	s_waitcnt vmcnt(0)
	v_readfirstlane_b32 s99, v3
	s_cmp_ge_u32 s99, 14
	s_cbranch_scc1 .Lxb_rel_14
	s_sleep 1
	s_sub_u32 s101, s101, 1
	s_cmp_lg_u32 s101, 0
	s_cbranch_scc1 .Lxb_spin_14

.LBB0_1447:
	s_cmp_gt_i32 s39, 15
	s_cselect_b64 s[0:1], -1, 0
	s_and_b64 s[2:3], s[8:9], s[0:1]
	s_andn2_b64 vcc, exec, s[2:3]
	s_cbranch_vccnz .LBB0_1459
	v_and_b32_e32 v1, 0x3fffffff, v0
	v_cmp_eq_u32_e32 vcc, 0, v1
	s_waitcnt vmcnt(0) lgkmcnt(0)
	s_barrier
	s_and_saveexec_b64 s[4:5], vcc
	s_cbranch_execz .LBB0_1458
	s_add_u32 s6, s84, 0x2ce12000
	s_addc_u32 s7, s85, 0
	s_getreg_b32 s98, hwreg(HW_REG_XCC_ID, 0, 4)
	s_lshl_b32 s99, s98, 7
	s_lshl_b32 s98, s98, 8
	v_mov_b32_e32 v1, s98
	v_mov_b32_e32 v3, s99
	v_mov_b32_e32 v4, 0
	v_mov_b32_e32 v2, 1
	global_load_dword v3, v3, s[6:7] offset:-2048 sc1
	global_atomic_add v4, v1, v2, s[6:7] sc0
	s_waitcnt vmcnt(0)
	v_readfirstlane_b32 s100, v3
	v_readfirstlane_b32 s99, v4
	s_mul_i32 s98, s100, 15
	s_add_i32 s99, s99, 1
	s_cmp_lg_u32 s99, s98
	s_cbranch_scc1 .Lxb_follow_15
	buffer_wbl2 sc1
	s_waitcnt vmcnt(0)
	v_mov_b32_e32 v4, 0
	global_atomic_add v2, v4, v3, s[6:7] offset:-4096 sc0
	s_waitcnt vmcnt(0)
	v_readfirstlane_b32 s99, v2
	s_add_i32 s99, s99, s100
	s_mul_i32 s98, s40, 15
	v_mov_b32_e32 v2, 1
	s_cmp_lg_u32 s99, s98
	s_cbranch_scc1 .Lxb_topwait_15
	global_atomic_add v4, v2, s[6:7] offset:-3840
	s_branch .Lxb_topdone_15

.Lxb_topspin_15:
	global_load_dword v3, v4, s[6:7] offset:-3840 sc1
	s_waitcnt vmcnt(0)
	v_readfirstlane_b32 s99, v3
	s_cmp_ge_u32 s99, 15
	s_cbranch_scc1 .Lxb_topdone_15
	s_sleep 1
	s_sub_u32 s101, s101, 1
	s_cmp_lg_u32 s101, 0
	s_cbranch_scc1 .Lxb_topspin_15

.Lxb_spin_15:
	global_load_dword v3, v1, s[6:7] offset:128 sc1
	s_waitcnt vmcnt(0)
	v_readfirstlane_b32 s99, v3
	s_cmp_ge_u32 s99, 15
	s_cbranch_scc1 .Lxb_rel_15
	s_sleep 1
	s_sub_u32 s101, s101, 1
	s_cmp_lg_u32 s101, 0
	s_cbranch_scc1 .Lxb_spin_15
